# fused-LN residual add via v_fma_mix_f32 straight from the loaded fp16 words (128 instead of 192 instructions per LN, bit-identical)
# speedup vs baseline: 1.0105x; 1.0105x over previous
;     __device__ __forceinline__ void fused(f32x4 (&acc)[2][2][4][2], const GUnit& u, int wr, int wc, int fr, int fq, LAS unsigned char* lds, int wid, int lane) const {
;         const int rl0 = wr * 64 + fr, cl0 = wc * 32 + 8 * fq, grow0 = u.pm * 256 + rl0, gcol0 = u.pn * 256 + cl0;
;         f16* H16 = (f16*)(ws + WS_H16);
;         { u32x4 hw[2][4][2];
; #pragma unroll
;         for (int ai = 0; ai < 2; ++ai)
; #pragma unroll
;             for (int m = 0; m < 4; ++m)
; #pragma unroll
;                 for (int bj = 0; bj < 2; ++bj) hw[ai][m][bj] = *(const u32x4*)(H16 + (size_t)(grow0 + ai * 128 + m * 16) * 1024 + gcol0 + bj * 128);
;         asm volatile("" ::: "memory");
; #pragma unroll
;         for (int ai = 0; ai < 2; ++ai)
; #pragma unroll
;             for (int m = 0; m < 4; ++m) {
; #pragma unroll
;                 for (int bj = 0; bj < 2; ++bj) { f32x4 h0, h1; unpk8(hw[ai][m][bj], h0, h1);
;                     acc[ai][bj][m][0] += ALPHA * h0; acc[ai][bj][m][1] += ALPHA * h1;
;                 }
;                 asm volatile("" : "+v"(acc[ai][0][m][0]), "+v"(acc[ai][0][m][1]), "+v"(acc[ai][1][m][0]), "+v"(acc[ai][1][m][1])); } }
.LBB0_432:
	s_andn2_b64 vcc, exec, s[2:3]
	s_cbranch_vccnz .LBB0_567
	v_mbcnt_lo_u32_b32 v32, -1, 0
	v_mbcnt_hi_u32_b32 v32, -1, v32
	s_lshl_b32 s2, s34, 8
	v_ashrrev_i32_e32 v34, 1, v32
	v_readlane_b32 s3, v251, 28
	v_and_or_b32 v233, v32, 15, s48
	v_and_b32_e32 v34, -8, v34
	s_lshl_b32 s14, s37, 8
	s_or_b32 s2, s2, s3
	v_add_u32_e32 v214, s14, v233
	v_add_u32_e32 v198, s2, v34
	v_readlane_b32 s2, v253, 4
	v_ashrrev_i32_e32 v199, 31, v198
	v_readlane_b32 s3, v253, 5
	v_ashrrev_i32_e32 v215, 31, v214
	v_lshlrev_b64 v[216:217], 11, v[214:215]
	v_lshl_add_u64 v[136:137], v[198:199], 1, s[2:3]
	v_lshl_add_u64 v[34:35], v[136:137], 0, v[216:217]
	global_load_dwordx4 v[192:195], v[34:35], off
	global_load_dwordx4 v[188:191], v[34:35], off offset:256
	v_or_b32_e32 v34, 16, v214
	v_ashrrev_i32_e32 v35, 31, v34
	v_lshlrev_b64 v[34:35], 11, v[34:35]
	v_lshl_add_u64 v[34:35], v[136:137], 0, v[34:35]
	global_load_dwordx4 v[184:187], v[34:35], off
	global_load_dwordx4 v[180:183], v[34:35], off offset:256
	v_or_b32_e32 v34, 32, v214
	v_ashrrev_i32_e32 v35, 31, v34
	v_lshlrev_b64 v[34:35], 11, v[34:35]
	v_lshl_add_u64 v[34:35], v[136:137], 0, v[34:35]
	global_load_dwordx4 v[176:179], v[34:35], off
	global_load_dwordx4 v[172:175], v[34:35], off offset:256
	v_or_b32_e32 v34, 48, v214
	v_ashrrev_i32_e32 v35, 31, v34
	v_lshlrev_b64 v[34:35], 11, v[34:35]
	v_lshl_add_u64 v[34:35], v[136:137], 0, v[34:35]
	global_load_dwordx4 v[168:171], v[34:35], off
	global_load_dwordx4 v[164:167], v[34:35], off offset:256
	v_add_u32_e32 v212, 0x80, v214
	v_ashrrev_i32_e32 v213, 31, v212
	v_lshlrev_b64 v[210:211], 11, v[212:213]
	v_lshl_add_u64 v[34:35], v[136:137], 0, v[210:211]
	global_load_dwordx4 v[160:163], v[34:35], off
	global_load_dwordx4 v[156:159], v[34:35], off offset:256
	v_add_u32_e32 v208, 0x90, v214
	v_ashrrev_i32_e32 v209, 31, v208
	v_lshlrev_b64 v[34:35], 11, v[208:209]
	v_lshl_add_u64 v[132:133], v[136:137], 0, v[34:35]
	global_load_dwordx4 v[152:155], v[132:133], off
	global_load_dwordx4 v[144:147], v[132:133], off offset:256
	v_add_u32_e32 v206, 0xa0, v214
	v_ashrrev_i32_e32 v207, 31, v206
	v_lshlrev_b64 v[204:205], 11, v[206:207]
	v_lshl_add_u64 v[132:133], v[136:137], 0, v[204:205]
	global_load_dwordx4 v[140:143], v[132:133], off
	s_nop 0
	global_load_dwordx4 v[132:135], v[132:133], off offset:256
	v_add_u32_e32 v200, 0xb0, v214
	v_ashrrev_i32_e32 v201, 31, v200
	v_lshlrev_b64 v[202:203], 11, v[200:201]
	v_lshl_add_u64 v[136:137], v[136:137], 0, v[202:203]
	global_load_dwordx4 v[148:151], v[136:137], off
	s_nop 0
	global_load_dwordx4 v[136:139], v[136:137], off offset:256
	s_waitcnt vmcnt(16)
	s_barrier
	s_mov_b32 s2, 0x3fd744fd
	v_mov_b32_e32 v226, 0x5800
	v_cmp_gt_u32_e32 vcc, 16, v32
	s_waitcnt vmcnt(0)
	v_fma_mix_f32 v130, v193, s2, v130 op_sel_hi:[1,0,0]
	v_fma_mix_f32 v131, v193, s2, v131 op_sel:[1,0,0] op_sel_hi:[1,0,0]
	v_fma_mix_f32 v126, v195, s2, v126 op_sel_hi:[1,0,0]
	v_fma_mix_f32 v127, v195, s2, v127 op_sel:[1,0,0] op_sel_hi:[1,0,0]
	v_fma_mix_f32 v122, v189, s2, v122 op_sel_hi:[1,0,0]
	v_fma_mix_f32 v123, v189, s2, v123 op_sel:[1,0,0] op_sel_hi:[1,0,0]
	v_fma_mix_f32 v118, v191, s2, v118 op_sel_hi:[1,0,0]
	v_fma_mix_f32 v119, v191, s2, v119 op_sel:[1,0,0] op_sel_hi:[1,0,0]
	v_fma_mix_f32 v114, v185, s2, v114 op_sel_hi:[1,0,0]
	v_fma_mix_f32 v115, v185, s2, v115 op_sel:[1,0,0] op_sel_hi:[1,0,0]
	v_fma_mix_f32 v110, v187, s2, v110 op_sel_hi:[1,0,0]
	v_fma_mix_f32 v111, v187, s2, v111 op_sel:[1,0,0] op_sel_hi:[1,0,0]
	v_fma_mix_f32 v106, v181, s2, v106 op_sel_hi:[1,0,0]
	v_fma_mix_f32 v107, v181, s2, v107 op_sel:[1,0,0] op_sel_hi:[1,0,0]
	v_fma_mix_f32 v102, v183, s2, v102 op_sel_hi:[1,0,0]
	v_fma_mix_f32 v103, v183, s2, v103 op_sel:[1,0,0] op_sel_hi:[1,0,0]
	v_fma_mix_f32 v98, v177, s2, v98 op_sel_hi:[1,0,0]
	v_fma_mix_f32 v99, v177, s2, v99 op_sel:[1,0,0] op_sel_hi:[1,0,0]
	v_fma_mix_f32 v94, v179, s2, v94 op_sel_hi:[1,0,0]
	v_fma_mix_f32 v95, v179, s2, v95 op_sel:[1,0,0] op_sel_hi:[1,0,0]
	v_fma_mix_f32 v90, v173, s2, v90 op_sel_hi:[1,0,0]
	v_fma_mix_f32 v91, v173, s2, v91 op_sel:[1,0,0] op_sel_hi:[1,0,0]
	v_fma_mix_f32 v86, v175, s2, v86 op_sel_hi:[1,0,0]
	v_fma_mix_f32 v87, v175, s2, v87 op_sel:[1,0,0] op_sel_hi:[1,0,0]
	v_fma_mix_f32 v82, v169, s2, v82 op_sel_hi:[1,0,0]
	v_fma_mix_f32 v83, v169, s2, v83 op_sel:[1,0,0] op_sel_hi:[1,0,0]
	v_fma_mix_f32 v78, v171, s2, v78 op_sel_hi:[1,0,0]
	v_fma_mix_f32 v79, v171, s2, v79 op_sel:[1,0,0] op_sel_hi:[1,0,0]
	v_fma_mix_f32 v74, v165, s2, v74 op_sel_hi:[1,0,0]
	v_fma_mix_f32 v75, v165, s2, v75 op_sel:[1,0,0] op_sel_hi:[1,0,0]
	v_fma_mix_f32 v70, v167, s2, v70 op_sel_hi:[1,0,0]
	v_fma_mix_f32 v71, v167, s2, v71 op_sel:[1,0,0] op_sel_hi:[1,0,0]
	v_fma_mix_f32 v66, v161, s2, v66 op_sel_hi:[1,0,0]
	v_fma_mix_f32 v67, v161, s2, v67 op_sel:[1,0,0] op_sel_hi:[1,0,0]
	v_fma_mix_f32 v62, v163, s2, v62 op_sel_hi:[1,0,0]
	v_fma_mix_f32 v63, v163, s2, v63 op_sel:[1,0,0] op_sel_hi:[1,0,0]
	v_fma_mix_f32 v58, v157, s2, v58 op_sel_hi:[1,0,0]
	v_fma_mix_f32 v59, v157, s2, v59 op_sel:[1,0,0] op_sel_hi:[1,0,0]
	v_fma_mix_f32 v54, v159, s2, v54 op_sel_hi:[1,0,0]
	v_fma_mix_f32 v55, v159, s2, v55 op_sel:[1,0,0] op_sel_hi:[1,0,0]
	v_fma_mix_f32 v50, v153, s2, v50 op_sel_hi:[1,0,0]
	v_fma_mix_f32 v51, v153, s2, v51 op_sel:[1,0,0] op_sel_hi:[1,0,0]
	v_fma_mix_f32 v46, v155, s2, v46 op_sel_hi:[1,0,0]
	v_fma_mix_f32 v47, v155, s2, v47 op_sel:[1,0,0] op_sel_hi:[1,0,0]
	v_fma_mix_f32 v42, v145, s2, v42 op_sel_hi:[1,0,0]
	v_fma_mix_f32 v43, v145, s2, v43 op_sel:[1,0,0] op_sel_hi:[1,0,0]
	v_fma_mix_f32 v38, v147, s2, v38 op_sel_hi:[1,0,0]
	v_fma_mix_f32 v39, v147, s2, v39 op_sel:[1,0,0] op_sel_hi:[1,0,0]
; #define LAS __attribute__((address_space(3)))
;     __device__ __forceinline__ void fused(f32x4 (&acc)[2][2][4][2], const GUnit& u, int wr, int wc, int fr, int fq, LAS unsigned char* lds, int wid, int lane) const {
;     ...
;         for (int ai = 0; ai < 2; ++ai)
; #pragma unroll
;             for (int m = 0; m < 4; ++m) {
; #pragma unroll
;                 for (int bj = 0; bj < 2; ++bj) { f32x4 h0, h1; unpk8(hw[ai][m][bj], h0, h1);
;                     acc[ai][bj][m][0] += ALPHA * h0; acc[ai][bj][m][1] += ALPHA * h1;
;                 }
;                 asm volatile("" : "+v"(acc[ai][0][m][0]), "+v"(acc[ai][0][m][1]), "+v"(acc[ai][1][m][0]), "+v"(acc[ai][1][m][1])); } }
;         LAS f32x2* P = (LAS f32x2*)lds; LAS f32x2* S = (LAS f32x2*)(lds + 8192); LAS unsigned* flag = (LAS unsigned*)(lds + 8192 + 2048);
;         unsigned* xbuf = (unsigned*)(ws + WS_X); unsigned* tmo = (unsigned*)(ws + WS_CTL) + CW_TMO;
; #pragma unroll
;         for (int ai = 0; ai < 2; ++ai)
; #pragma unroll
;             for (int m = 0; m < 4; ++m) {
;                 float s = 0.f;
; #pragma unroll
;                 for (int bj = 0; bj < 2; ++bj)
; #pragma unroll
;                     for (int n = 0; n < 2; ++n) { const f32x4 x = acc[ai][bj][m][n]; s += (x[0] + x[1]) + (x[2] + x[3]); }
	v_fma_mix_f32 v30, v141, s2, v30 op_sel_hi:[1,0,0]
	v_fma_mix_f32 v31, v141, s2, v31 op_sel:[1,0,0] op_sel_hi:[1,0,0]
	v_fma_mix_f32 v26, v143, s2, v26 op_sel_hi:[1,0,0]
	v_fma_mix_f32 v27, v143, s2, v27 op_sel:[1,0,0] op_sel_hi:[1,0,0]
	v_fma_mix_f32 v22, v133, s2, v22 op_sel_hi:[1,0,0]
	v_fma_mix_f32 v23, v133, s2, v23 op_sel:[1,0,0] op_sel_hi:[1,0,0]
	v_fma_mix_f32 v18, v135, s2, v18 op_sel_hi:[1,0,0]
	v_fma_mix_f32 v19, v135, s2, v19 op_sel:[1,0,0] op_sel_hi:[1,0,0]
	v_fma_mix_f32 v12, v148, s2, v12 op_sel_hi:[1,0,0]
	v_fma_mix_f32 v13, v148, s2, v13 op_sel:[1,0,0] op_sel_hi:[1,0,0]
	v_fma_mix_f32 v14, v149, s2, v14 op_sel_hi:[1,0,0]
	v_fma_mix_f32 v15, v149, s2, v15 op_sel:[1,0,0] op_sel_hi:[1,0,0]
	v_fma_mix_f32 v128, v192, s2, v128 op_sel_hi:[1,0,0]
	v_fma_mix_f32 v129, v192, s2, v129 op_sel:[1,0,0] op_sel_hi:[1,0,0]
	v_fma_mix_f32 v124, v194, s2, v124 op_sel_hi:[1,0,0]
	v_fma_mix_f32 v125, v194, s2, v125 op_sel:[1,0,0] op_sel_hi:[1,0,0]
	v_fma_mix_f32 v120, v188, s2, v120 op_sel_hi:[1,0,0]
	v_fma_mix_f32 v121, v188, s2, v121 op_sel:[1,0,0] op_sel_hi:[1,0,0]
	v_fma_mix_f32 v116, v190, s2, v116 op_sel_hi:[1,0,0]
	v_fma_mix_f32 v117, v190, s2, v117 op_sel:[1,0,0] op_sel_hi:[1,0,0]
	v_fma_mix_f32 v6, v137, s2, v6 op_sel_hi:[1,0,0]
	v_fma_mix_f32 v7, v137, s2, v7 op_sel:[1,0,0] op_sel_hi:[1,0,0]
	v_fma_mix_f32 v4, v136, s2, v4 op_sel_hi:[1,0,0]
	v_fma_mix_f32 v5, v136, s2, v5 op_sel:[1,0,0] op_sel_hi:[1,0,0]
	v_fma_mix_f32 v0, v138, s2, v0 op_sel_hi:[1,0,0]
	v_fma_mix_f32 v1, v138, s2, v1 op_sel:[1,0,0] op_sel_hi:[1,0,0]
	v_fma_mix_f32 v20, v132, s2, v20 op_sel_hi:[1,0,0]
	v_fma_mix_f32 v21, v132, s2, v21 op_sel:[1,0,0] op_sel_hi:[1,0,0]
	v_fma_mix_f32 v16, v134, s2, v16 op_sel_hi:[1,0,0]
	v_fma_mix_f32 v17, v134, s2, v17 op_sel:[1,0,0] op_sel_hi:[1,0,0]
	v_fma_mix_f32 v2, v139, s2, v2 op_sel_hi:[1,0,0]
	v_fma_mix_f32 v3, v139, s2, v3 op_sel:[1,0,0] op_sel_hi:[1,0,0]
	v_fma_mix_f32 v112, v184, s2, v112 op_sel_hi:[1,0,0]
	v_fma_mix_f32 v113, v184, s2, v113 op_sel:[1,0,0] op_sel_hi:[1,0,0]
	v_fma_mix_f32 v108, v186, s2, v108 op_sel_hi:[1,0,0]
	v_fma_mix_f32 v109, v186, s2, v109 op_sel:[1,0,0] op_sel_hi:[1,0,0]
	v_fma_mix_f32 v104, v180, s2, v104 op_sel_hi:[1,0,0]
	v_fma_mix_f32 v105, v180, s2, v105 op_sel:[1,0,0] op_sel_hi:[1,0,0]
	v_fma_mix_f32 v100, v182, s2, v100 op_sel_hi:[1,0,0]
	v_fma_mix_f32 v101, v182, s2, v101 op_sel:[1,0,0] op_sel_hi:[1,0,0]
	v_fma_mix_f32 v96, v176, s2, v96 op_sel_hi:[1,0,0]
	v_fma_mix_f32 v97, v176, s2, v97 op_sel:[1,0,0] op_sel_hi:[1,0,0]
	v_fma_mix_f32 v92, v178, s2, v92 op_sel_hi:[1,0,0]
	v_fma_mix_f32 v93, v178, s2, v93 op_sel:[1,0,0] op_sel_hi:[1,0,0]
	v_fma_mix_f32 v88, v172, s2, v88 op_sel_hi:[1,0,0]
	v_fma_mix_f32 v89, v172, s2, v89 op_sel:[1,0,0] op_sel_hi:[1,0,0]
	v_fma_mix_f32 v84, v174, s2, v84 op_sel_hi:[1,0,0]
	v_fma_mix_f32 v85, v174, s2, v85 op_sel:[1,0,0] op_sel_hi:[1,0,0]
	v_fma_mix_f32 v80, v168, s2, v80 op_sel_hi:[1,0,0]
	v_fma_mix_f32 v81, v168, s2, v81 op_sel:[1,0,0] op_sel_hi:[1,0,0]
	v_fma_mix_f32 v76, v170, s2, v76 op_sel_hi:[1,0,0]
	v_fma_mix_f32 v77, v170, s2, v77 op_sel:[1,0,0] op_sel_hi:[1,0,0]
	v_fma_mix_f32 v72, v164, s2, v72 op_sel_hi:[1,0,0]
	v_fma_mix_f32 v73, v164, s2, v73 op_sel:[1,0,0] op_sel_hi:[1,0,0]
	v_fma_mix_f32 v68, v166, s2, v68 op_sel_hi:[1,0,0]
	v_fma_mix_f32 v69, v166, s2, v69 op_sel:[1,0,0] op_sel_hi:[1,0,0]
	v_fma_mix_f32 v64, v160, s2, v64 op_sel_hi:[1,0,0]
	v_fma_mix_f32 v65, v160, s2, v65 op_sel:[1,0,0] op_sel_hi:[1,0,0]
	v_fma_mix_f32 v60, v162, s2, v60 op_sel_hi:[1,0,0]
	v_fma_mix_f32 v61, v162, s2, v61 op_sel:[1,0,0] op_sel_hi:[1,0,0]
	v_fma_mix_f32 v56, v156, s2, v56 op_sel_hi:[1,0,0]
	v_fma_mix_f32 v57, v156, s2, v57 op_sel:[1,0,0] op_sel_hi:[1,0,0]
	v_fma_mix_f32 v52, v158, s2, v52 op_sel_hi:[1,0,0]
	v_fma_mix_f32 v53, v158, s2, v53 op_sel:[1,0,0] op_sel_hi:[1,0,0]
	v_fma_mix_f32 v48, v152, s2, v48 op_sel_hi:[1,0,0]
	v_fma_mix_f32 v49, v152, s2, v49 op_sel:[1,0,0] op_sel_hi:[1,0,0]
	v_fma_mix_f32 v44, v154, s2, v44 op_sel_hi:[1,0,0]
	v_fma_mix_f32 v45, v154, s2, v45 op_sel:[1,0,0] op_sel_hi:[1,0,0]
	v_fma_mix_f32 v40, v144, s2, v40 op_sel_hi:[1,0,0]
	v_fma_mix_f32 v41, v144, s2, v41 op_sel:[1,0,0] op_sel_hi:[1,0,0]
	v_fma_mix_f32 v36, v146, s2, v36 op_sel_hi:[1,0,0]
	v_fma_mix_f32 v37, v146, s2, v37 op_sel:[1,0,0] op_sel_hi:[1,0,0]
	v_fma_mix_f32 v28, v140, s2, v28 op_sel_hi:[1,0,0]
	v_fma_mix_f32 v29, v140, s2, v29 op_sel:[1,0,0] op_sel_hi:[1,0,0]
	v_fma_mix_f32 v24, v142, s2, v24 op_sel_hi:[1,0,0]
	v_fma_mix_f32 v25, v142, s2, v25 op_sel:[1,0,0] op_sel_hi:[1,0,0]
	v_fma_mix_f32 v10, v151, s2, v10 op_sel_hi:[1,0,0]
	v_fma_mix_f32 v11, v151, s2, v11 op_sel:[1,0,0] op_sel_hi:[1,0,0]
	v_fma_mix_f32 v8, v150, s2, v8 op_sel_hi:[1,0,0]
	v_fma_mix_f32 v9, v150, s2, v9 op_sel:[1,0,0] op_sel_hi:[1,0,0]
	v_readlane_b32 s2, v252, 13
	v_cmp_gt_u32_e32 vcc, 16, v32
	v_pk_add_f32 v[136:137], v[128:129], v[130:131]
	v_pk_add_f32 v[150:151], v[112:113], v[114:115]
	v_pk_add_f32 v[164:165], v[96:97], v[98:99]
	v_pk_add_f32 v[178:179], v[80:81], v[82:83]
	v_pk_add_f32 v[138:139], v[124:125], v[126:127]
	v_pk_add_f32 v[152:153], v[108:109], v[110:111]
	v_pk_add_f32 v[166:167], v[92:93], v[94:95]
	v_pk_add_f32 v[180:181], v[76:77], v[78:79]
	v_pk_add_f32 v[140:141], v[120:121], v[122:123]
	v_pk_add_f32 v[154:155], v[104:105], v[106:107]
	v_pk_add_f32 v[168:169], v[88:89], v[90:91]
	v_pk_add_f32 v[182:183], v[72:73], v[74:75]
	v_pk_add_f32 v[142:143], v[116:117], v[118:119]
	v_pk_add_f32 v[156:157], v[100:101], v[102:103]
	v_pk_add_f32 v[170:171], v[84:85], v[86:87]
	v_pk_add_f32 v[184:185], v[68:69], v[70:71]
	v_pk_add_f32 v[136:137], v[136:137], v[138:139]
; __device__ __forceinline__ float shx(float v, int mask) { return __builtin_bit_cast(float, __builtin_amdgcn_ds_bpermute((lane_now() ^ mask) << 2, __builtin_bit_cast(int, v))); }
;     __device__ __forceinline__ void fused(f32x4 (&acc)[2][2][4][2], const GUnit& u, int wr, int wc, int fr, int fq, LAS unsigned char* lds, int wid, int lane) const {
;     ...
;                 float s = 0.f;
; #pragma unroll
;                 for (int bj = 0; bj < 2; ++bj)
; #pragma unroll
;                     for (int n = 0; n < 2; ++n) { const f32x4 x = acc[ai][bj][m][n]; s += (x[0] + x[1]) + (x[2] + x[3]); }
;                 s += shx(s, 16); s += shx(s, 32);
;                 const float mw = s * (1.0f / 64.0f); float q = 0.f;
; #pragma unroll
;                 for (int bj = 0; bj < 2; ++bj)
; #pragma unroll
;                     for (int n = 0; n < 2; ++n) { const f32x4 d = acc[ai][bj][m][n] - mw; q += (d[0] * d[0] + d[1] * d[1]) + (d[2] * d[2] + d[3] * d[3]); }
;                 q += shx(q, 16); q += shx(q, 32);
	v_pk_add_f32 v[150:151], v[150:151], v[152:153]
	v_pk_add_f32 v[164:165], v[164:165], v[166:167]
	v_pk_add_f32 v[178:179], v[178:179], v[180:181]
	v_pk_add_f32 v[140:141], v[140:141], v[142:143]
	v_pk_add_f32 v[154:155], v[154:155], v[156:157]
	v_pk_add_f32 v[168:169], v[168:169], v[170:171]
	v_pk_add_f32 v[182:183], v[182:183], v[184:185]
	v_pk_add_f32 v[136:137], v[136:137], v[140:141]
	v_pk_add_f32 v[150:151], v[150:151], v[154:155]
	v_pk_add_f32 v[164:165], v[164:165], v[168:169]
	v_pk_add_f32 v[178:179], v[178:179], v[182:183]
	v_add_f32_e32 v145, v136, v137
	v_add_f32_e32 v159, v150, v151
	v_add_f32_e32 v173, v164, v165
	v_add_f32_e32 v187, v178, v179
	v_mov_b32_e32 v148, v145
	v_mov_b32_e32 v162, v159
	v_mov_b32_e32 v176, v173
	v_mov_b32_e32 v190, v187
	v_permlane16_swap_b32 v148, v145
	v_permlane16_swap_b32 v162, v159
	v_permlane16_swap_b32 v176, v173
	v_permlane16_swap_b32 v190, v187
	v_add_f32_e32 v145, v145, v148
	v_add_f32_e32 v159, v159, v162
	v_add_f32_e32 v173, v173, v176
	v_add_f32_e32 v187, v187, v190
	v_mov_b32_e32 v148, v145
	v_mov_b32_e32 v162, v159
	v_mov_b32_e32 v176, v173
	v_mov_b32_e32 v190, v187
	v_permlane32_swap_b32 v148, v145
	v_permlane32_swap_b32 v162, v159
	v_permlane32_swap_b32 v176, v173
	v_permlane32_swap_b32 v190, v187
	v_add_f32_e32 v145, v145, v148
	v_add_f32_e32 v159, v159, v162
	v_add_f32_e32 v173, v173, v176
	v_add_f32_e32 v187, v187, v190
	v_mul_f32_e32 v144, 0x3c800000, v145
	v_mul_f32_e32 v158, 0x3c800000, v159
	v_mul_f32_e32 v172, 0x3c800000, v173
	v_mul_f32_e32 v186, 0x3c800000, v187
	v_pk_add_f32 v[136:137], v[128:129], v[144:145] op_sel_hi:[1,0] neg_lo:[0,1] neg_hi:[0,1]
	v_pk_add_f32 v[150:151], v[112:113], v[158:159] op_sel_hi:[1,0] neg_lo:[0,1] neg_hi:[0,1]
	v_pk_add_f32 v[164:165], v[96:97], v[172:173] op_sel_hi:[1,0] neg_lo:[0,1] neg_hi:[0,1]
	v_pk_add_f32 v[178:179], v[80:81], v[186:187] op_sel_hi:[1,0] neg_lo:[0,1] neg_hi:[0,1]
	v_pk_mul_f32 v[146:147], v[136:137], v[136:137]
	v_pk_mul_f32 v[160:161], v[150:151], v[150:151]
	v_pk_mul_f32 v[174:175], v[164:165], v[164:165]
	v_pk_mul_f32 v[188:189], v[178:179], v[178:179]
	v_pk_add_f32 v[138:139], v[130:131], v[144:145] op_sel_hi:[1,0] neg_lo:[0,1] neg_hi:[0,1]
	v_pk_add_f32 v[152:153], v[114:115], v[158:159] op_sel_hi:[1,0] neg_lo:[0,1] neg_hi:[0,1]
	v_pk_add_f32 v[166:167], v[98:99], v[172:173] op_sel_hi:[1,0] neg_lo:[0,1] neg_hi:[0,1]
	v_pk_add_f32 v[180:181], v[82:83], v[186:187] op_sel_hi:[1,0] neg_lo:[0,1] neg_hi:[0,1]
	v_pk_fma_f32 v[146:147], v[138:139], v[138:139], v[146:147]
	v_pk_fma_f32 v[160:161], v[152:153], v[152:153], v[160:161]
	v_pk_fma_f32 v[174:175], v[166:167], v[166:167], v[174:175]
	v_pk_fma_f32 v[188:189], v[180:181], v[180:181], v[188:189]
	v_pk_add_f32 v[140:141], v[124:125], v[144:145] op_sel_hi:[1,0] neg_lo:[0,1] neg_hi:[0,1]
	v_pk_add_f32 v[154:155], v[108:109], v[158:159] op_sel_hi:[1,0] neg_lo:[0,1] neg_hi:[0,1]
	v_pk_add_f32 v[168:169], v[92:93], v[172:173] op_sel_hi:[1,0] neg_lo:[0,1] neg_hi:[0,1]
	v_pk_add_f32 v[182:183], v[76:77], v[186:187] op_sel_hi:[1,0] neg_lo:[0,1] neg_hi:[0,1]
	v_pk_fma_f32 v[146:147], v[140:141], v[140:141], v[146:147]
	v_pk_fma_f32 v[160:161], v[154:155], v[154:155], v[160:161]
	v_pk_fma_f32 v[174:175], v[168:169], v[168:169], v[174:175]
	v_pk_fma_f32 v[188:189], v[182:183], v[182:183], v[188:189]
	v_pk_add_f32 v[142:143], v[126:127], v[144:145] op_sel_hi:[1,0] neg_lo:[0,1] neg_hi:[0,1]
	v_pk_add_f32 v[156:157], v[110:111], v[158:159] op_sel_hi:[1,0] neg_lo:[0,1] neg_hi:[0,1]
	v_pk_add_f32 v[170:171], v[94:95], v[172:173] op_sel_hi:[1,0] neg_lo:[0,1] neg_hi:[0,1]
	v_pk_add_f32 v[184:185], v[78:79], v[186:187] op_sel_hi:[1,0] neg_lo:[0,1] neg_hi:[0,1]
	v_pk_fma_f32 v[146:147], v[142:143], v[142:143], v[146:147]
	v_pk_fma_f32 v[160:161], v[156:157], v[156:157], v[160:161]
	v_pk_fma_f32 v[174:175], v[170:171], v[170:171], v[174:175]
	v_pk_fma_f32 v[188:189], v[184:185], v[184:185], v[188:189]
	v_pk_add_f32 v[136:137], v[120:121], v[144:145] op_sel_hi:[1,0] neg_lo:[0,1] neg_hi:[0,1]
	v_pk_add_f32 v[150:151], v[104:105], v[158:159] op_sel_hi:[1,0] neg_lo:[0,1] neg_hi:[0,1]
	v_pk_add_f32 v[164:165], v[88:89], v[172:173] op_sel_hi:[1,0] neg_lo:[0,1] neg_hi:[0,1]
	v_pk_add_f32 v[178:179], v[72:73], v[186:187] op_sel_hi:[1,0] neg_lo:[0,1] neg_hi:[0,1]
	v_pk_fma_f32 v[146:147], v[136:137], v[136:137], v[146:147]
	v_pk_fma_f32 v[160:161], v[150:151], v[150:151], v[160:161]
	v_pk_fma_f32 v[174:175], v[164:165], v[164:165], v[174:175]
	v_pk_fma_f32 v[188:189], v[178:179], v[178:179], v[188:189]
	v_pk_add_f32 v[138:139], v[122:123], v[144:145] op_sel_hi:[1,0] neg_lo:[0,1] neg_hi:[0,1]
	v_pk_add_f32 v[152:153], v[106:107], v[158:159] op_sel_hi:[1,0] neg_lo:[0,1] neg_hi:[0,1]
	v_pk_add_f32 v[166:167], v[90:91], v[172:173] op_sel_hi:[1,0] neg_lo:[0,1] neg_hi:[0,1]
	v_pk_add_f32 v[180:181], v[74:75], v[186:187] op_sel_hi:[1,0] neg_lo:[0,1] neg_hi:[0,1]
	v_pk_fma_f32 v[146:147], v[138:139], v[138:139], v[146:147]
	v_pk_fma_f32 v[160:161], v[152:153], v[152:153], v[160:161]
	v_pk_fma_f32 v[174:175], v[166:167], v[166:167], v[174:175]
	v_pk_fma_f32 v[188:189], v[180:181], v[180:181], v[188:189]
	v_pk_add_f32 v[140:141], v[116:117], v[144:145] op_sel_hi:[1,0] neg_lo:[0,1] neg_hi:[0,1]
	v_pk_add_f32 v[154:155], v[100:101], v[158:159] op_sel_hi:[1,0] neg_lo:[0,1] neg_hi:[0,1]
	v_pk_add_f32 v[168:169], v[84:85], v[172:173] op_sel_hi:[1,0] neg_lo:[0,1] neg_hi:[0,1]
	v_pk_add_f32 v[182:183], v[68:69], v[186:187] op_sel_hi:[1,0] neg_lo:[0,1] neg_hi:[0,1]
	v_pk_fma_f32 v[146:147], v[140:141], v[140:141], v[146:147]
	v_pk_fma_f32 v[160:161], v[154:155], v[154:155], v[160:161]
; __device__ __forceinline__ float shx(float v, int mask) { return __builtin_bit_cast(float, __builtin_amdgcn_ds_bpermute((lane_now() ^ mask) << 2, __builtin_bit_cast(int, v))); }
;     __device__ __forceinline__ void fused(f32x4 (&acc)[2][2][4][2], const GUnit& u, int wr, int wc, int fr, int fq, LAS unsigned char* lds, int wid, int lane) const {
;     ...
;                     for (int n = 0; n < 2; ++n) { const f32x4 x = acc[ai][bj][m][n]; s += (x[0] + x[1]) + (x[2] + x[3]); }
;                 s += shx(s, 16); s += shx(s, 32);
;                 const float mw = s * (1.0f / 64.0f); float q = 0.f;
; #pragma unroll
;                 for (int bj = 0; bj < 2; ++bj)
; #pragma unroll
;                     for (int n = 0; n < 2; ++n) { const f32x4 d = acc[ai][bj][m][n] - mw; q += (d[0] * d[0] + d[1] * d[1]) + (d[2] * d[2] + d[3] * d[3]); }
;                 q += shx(q, 16); q += shx(q, 32);
;                 if (fq == 0) P[(ai * 128 + wr * 64 + m * 16 + fr) * 4 + wc] = (f32x2){mw, q};
	v_pk_fma_f32 v[174:175], v[168:169], v[168:169], v[174:175]
	v_pk_fma_f32 v[188:189], v[182:183], v[182:183], v[188:189]
	v_pk_add_f32 v[142:143], v[118:119], v[144:145] op_sel_hi:[1,0] neg_lo:[0,1] neg_hi:[0,1]
	v_pk_add_f32 v[156:157], v[102:103], v[158:159] op_sel_hi:[1,0] neg_lo:[0,1] neg_hi:[0,1]
	v_pk_add_f32 v[170:171], v[86:87], v[172:173] op_sel_hi:[1,0] neg_lo:[0,1] neg_hi:[0,1]
	v_pk_add_f32 v[184:185], v[70:71], v[186:187] op_sel_hi:[1,0] neg_lo:[0,1] neg_hi:[0,1]
	v_pk_fma_f32 v[146:147], v[142:143], v[142:143], v[146:147]
	v_pk_fma_f32 v[160:161], v[156:157], v[156:157], v[160:161]
	v_pk_fma_f32 v[174:175], v[170:171], v[170:171], v[174:175]
	v_pk_fma_f32 v[188:189], v[184:185], v[184:185], v[188:189]
	v_add_f32_e32 v145, v146, v147
	v_add_f32_e32 v159, v160, v161
	v_add_f32_e32 v173, v174, v175
	v_add_f32_e32 v187, v188, v189
	v_mov_b32_e32 v148, v145
	v_mov_b32_e32 v162, v159
	v_mov_b32_e32 v176, v173
	v_mov_b32_e32 v190, v187
	v_permlane16_swap_b32 v148, v145
	v_permlane16_swap_b32 v162, v159
	v_permlane16_swap_b32 v176, v173
	v_permlane16_swap_b32 v190, v187
	v_add_f32_e32 v145, v145, v148
	v_add_f32_e32 v159, v159, v162
	v_add_f32_e32 v173, v173, v176
	v_add_f32_e32 v187, v187, v190
	v_mov_b32_e32 v148, v145
	v_mov_b32_e32 v162, v159
	v_mov_b32_e32 v176, v173
	v_mov_b32_e32 v190, v187
	v_permlane32_swap_b32 v148, v145
	v_permlane32_swap_b32 v162, v159
	v_permlane32_swap_b32 v176, v173
	v_permlane32_swap_b32 v190, v187
	v_add_f32_e32 v145, v145, v148
	v_add_f32_e32 v159, v159, v162
	v_add_f32_e32 v173, v173, v176
	v_add_f32_e32 v187, v187, v190
	v_lshl_add_u32 v132, v233, 5, s2
	s_and_saveexec_b64 s[4:5], vcc
	ds_write_b64 v132, v[144:145]
	ds_write_b64 v132, v[158:159] offset:512
	ds_write_b64 v132, v[172:173] offset:1024
	ds_write_b64 v132, v[186:187] offset:1536
	s_or_b64 exec, exec, s[4:5]
	v_pk_add_f32 v[136:137], v[64:65], v[66:67]
	v_pk_add_f32 v[150:151], v[48:49], v[50:51]
	v_pk_add_f32 v[164:165], v[28:29], v[30:31]
	v_pk_add_f32 v[178:179], v[12:13], v[14:15]
	v_pk_add_f32 v[138:139], v[60:61], v[62:63]
	v_pk_add_f32 v[152:153], v[44:45], v[46:47]
	v_pk_add_f32 v[166:167], v[24:25], v[26:27]
	v_pk_add_f32 v[180:181], v[8:9], v[10:11]
	v_pk_add_f32 v[140:141], v[56:57], v[58:59]
	v_pk_add_f32 v[154:155], v[40:41], v[42:43]
	v_pk_add_f32 v[168:169], v[20:21], v[22:23]
	v_pk_add_f32 v[182:183], v[4:5], v[6:7]
	v_pk_add_f32 v[142:143], v[52:53], v[54:55]
	v_pk_add_f32 v[156:157], v[36:37], v[38:39]
	v_pk_add_f32 v[170:171], v[16:17], v[18:19]
	v_pk_add_f32 v[184:185], v[0:1], v[2:3]
	v_pk_add_f32 v[136:137], v[136:137], v[138:139]
	v_pk_add_f32 v[150:151], v[150:151], v[152:153]
	v_pk_add_f32 v[164:165], v[164:165], v[166:167]
	v_pk_add_f32 v[178:179], v[178:179], v[180:181]
	v_pk_add_f32 v[140:141], v[140:141], v[142:143]
	v_pk_add_f32 v[154:155], v[154:155], v[156:157]
	v_pk_add_f32 v[168:169], v[168:169], v[170:171]
	v_pk_add_f32 v[182:183], v[182:183], v[184:185]
	v_pk_add_f32 v[136:137], v[136:137], v[140:141]
	v_pk_add_f32 v[150:151], v[150:151], v[154:155]
	v_pk_add_f32 v[164:165], v[164:165], v[168:169]
	v_pk_add_f32 v[178:179], v[178:179], v[182:183]
	v_add_f32_e32 v145, v136, v137
	v_add_f32_e32 v159, v150, v151
	v_add_f32_e32 v173, v164, v165
	v_add_f32_e32 v187, v178, v179
	v_mov_b32_e32 v148, v145
	v_mov_b32_e32 v162, v159
	v_mov_b32_e32 v176, v173
	v_mov_b32_e32 v190, v187
	v_permlane16_swap_b32 v148, v145
	v_permlane16_swap_b32 v162, v159
	v_permlane16_swap_b32 v176, v173
	v_permlane16_swap_b32 v190, v187
	v_add_f32_e32 v145, v145, v148
	v_add_f32_e32 v159, v159, v162
	v_add_f32_e32 v173, v173, v176
	v_add_f32_e32 v187, v187, v190
	v_mov_b32_e32 v148, v145
	v_mov_b32_e32 v162, v159
	v_mov_b32_e32 v176, v173
	v_mov_b32_e32 v190, v187
	v_permlane32_swap_b32 v148, v145
	v_permlane32_swap_b32 v162, v159
	v_permlane32_swap_b32 v176, v173
	v_permlane32_swap_b32 v190, v187
	v_add_f32_e32 v145, v145, v148
	v_add_f32_e32 v159, v159, v162
	v_add_f32_e32 v173, v173, v176
	v_add_f32_e32 v187, v187, v190
	v_mul_f32_e32 v144, 0x3c800000, v145
	v_mul_f32_e32 v158, 0x3c800000, v159
	v_mul_f32_e32 v172, 0x3c800000, v173
	v_mul_f32_e32 v186, 0x3c800000, v187
	v_pk_add_f32 v[136:137], v[64:65], v[144:145] op_sel_hi:[1,0] neg_lo:[0,1] neg_hi:[0,1]
	v_pk_add_f32 v[150:151], v[48:49], v[158:159] op_sel_hi:[1,0] neg_lo:[0,1] neg_hi:[0,1]
	v_pk_add_f32 v[164:165], v[28:29], v[172:173] op_sel_hi:[1,0] neg_lo:[0,1] neg_hi:[0,1]
	v_pk_add_f32 v[178:179], v[12:13], v[186:187] op_sel_hi:[1,0] neg_lo:[0,1] neg_hi:[0,1]
	v_pk_mul_f32 v[146:147], v[136:137], v[136:137]
	v_pk_mul_f32 v[160:161], v[150:151], v[150:151]
	v_pk_mul_f32 v[174:175], v[164:165], v[164:165]
	v_pk_mul_f32 v[188:189], v[178:179], v[178:179]
	v_pk_add_f32 v[138:139], v[66:67], v[144:145] op_sel_hi:[1,0] neg_lo:[0,1] neg_hi:[0,1]
	v_pk_add_f32 v[152:153], v[50:51], v[158:159] op_sel_hi:[1,0] neg_lo:[0,1] neg_hi:[0,1]
	v_pk_add_f32 v[166:167], v[30:31], v[172:173] op_sel_hi:[1,0] neg_lo:[0,1] neg_hi:[0,1]
	v_pk_add_f32 v[180:181], v[14:15], v[186:187] op_sel_hi:[1,0] neg_lo:[0,1] neg_hi:[0,1]
	v_pk_fma_f32 v[146:147], v[138:139], v[138:139], v[146:147]
	v_pk_fma_f32 v[160:161], v[152:153], v[152:153], v[160:161]
	v_pk_fma_f32 v[174:175], v[166:167], v[166:167], v[174:175]
	v_pk_fma_f32 v[188:189], v[180:181], v[180:181], v[188:189]
	v_pk_add_f32 v[140:141], v[60:61], v[144:145] op_sel_hi:[1,0] neg_lo:[0,1] neg_hi:[0,1]
	v_pk_add_f32 v[154:155], v[44:45], v[158:159] op_sel_hi:[1,0] neg_lo:[0,1] neg_hi:[0,1]
	v_pk_add_f32 v[168:169], v[24:25], v[172:173] op_sel_hi:[1,0] neg_lo:[0,1] neg_hi:[0,1]
	v_pk_add_f32 v[182:183], v[8:9], v[186:187] op_sel_hi:[1,0] neg_lo:[0,1] neg_hi:[0,1]
; __device__ __forceinline__ float shx(float v, int mask) { return __builtin_bit_cast(float, __builtin_amdgcn_ds_bpermute((lane_now() ^ mask) << 2, __builtin_bit_cast(int, v))); }
;     __device__ __forceinline__ void fused(f32x4 (&acc)[2][2][4][2], const GUnit& u, int wr, int wc, int fr, int fq, LAS unsigned char* lds, int wid, int lane) const {
;     ...
;                     for (int n = 0; n < 2; ++n) { const f32x4 d = acc[ai][bj][m][n] - mw; q += (d[0] * d[0] + d[1] * d[1]) + (d[2] * d[2] + d[3] * d[3]); }
;                 q += shx(q, 16); q += shx(q, 32);
;                 if (fq == 0) P[(ai * 128 + wr * 64 + m * 16 + fr) * 4 + wc] = (f32x2){mw, q};
;             }
;         asm volatile("s_waitcnt lgkmcnt(0)" ::: "memory"); __builtin_amdgcn_s_barrier(); asm volatile("" ::: "memory");
;         const int prow = wid * 32 + (lane & 31);
;         if (lane < 32) {
;             const f32x2 a = P[prow * 4 + 0], b = P[prow * 4 + 1], c = P[prow * 4 + 2], d = P[prow * 4 + 3];
;             const float mt = (a.x + b.x + c.x + d.x) * 0.25f;
;             const float da = a.x - mt, db = b.x - mt, dc = c.x - mt, dd = d.x - mt;
;             const float m2 = (a.y + b.y) + (c.y + d.y) + 64.0f * ((da * da + db * db) + (dc * dc + dd * dd));
;             unsigned long long* slot = (unsigned long long*)xbuf + ((size_t)(u.pm * 256 + prow) * 4 + u.pn);
;             __hip_atomic_store(slot, ((unsigned long long)__float_as_uint(m2) << 32) | __float_as_uint(mt), __ATOMIC_RELAXED, __HIP_MEMORY_SCOPE_AGENT);
	v_pk_fma_f32 v[146:147], v[140:141], v[140:141], v[146:147]
	v_pk_fma_f32 v[160:161], v[154:155], v[154:155], v[160:161]
	v_pk_fma_f32 v[174:175], v[168:169], v[168:169], v[174:175]
	v_pk_fma_f32 v[188:189], v[182:183], v[182:183], v[188:189]
	v_pk_add_f32 v[142:143], v[62:63], v[144:145] op_sel_hi:[1,0] neg_lo:[0,1] neg_hi:[0,1]
	v_pk_add_f32 v[156:157], v[46:47], v[158:159] op_sel_hi:[1,0] neg_lo:[0,1] neg_hi:[0,1]
	v_pk_add_f32 v[170:171], v[26:27], v[172:173] op_sel_hi:[1,0] neg_lo:[0,1] neg_hi:[0,1]
	v_pk_add_f32 v[184:185], v[10:11], v[186:187] op_sel_hi:[1,0] neg_lo:[0,1] neg_hi:[0,1]
	v_pk_fma_f32 v[146:147], v[142:143], v[142:143], v[146:147]
	v_pk_fma_f32 v[160:161], v[156:157], v[156:157], v[160:161]
	v_pk_fma_f32 v[174:175], v[170:171], v[170:171], v[174:175]
	v_pk_fma_f32 v[188:189], v[184:185], v[184:185], v[188:189]
	v_pk_add_f32 v[136:137], v[56:57], v[144:145] op_sel_hi:[1,0] neg_lo:[0,1] neg_hi:[0,1]
	v_pk_add_f32 v[150:151], v[40:41], v[158:159] op_sel_hi:[1,0] neg_lo:[0,1] neg_hi:[0,1]
	v_pk_add_f32 v[164:165], v[20:21], v[172:173] op_sel_hi:[1,0] neg_lo:[0,1] neg_hi:[0,1]
	v_pk_add_f32 v[178:179], v[4:5], v[186:187] op_sel_hi:[1,0] neg_lo:[0,1] neg_hi:[0,1]
	v_pk_fma_f32 v[146:147], v[136:137], v[136:137], v[146:147]
	v_pk_fma_f32 v[160:161], v[150:151], v[150:151], v[160:161]
	v_pk_fma_f32 v[174:175], v[164:165], v[164:165], v[174:175]
	v_pk_fma_f32 v[188:189], v[178:179], v[178:179], v[188:189]
	v_pk_add_f32 v[138:139], v[58:59], v[144:145] op_sel_hi:[1,0] neg_lo:[0,1] neg_hi:[0,1]
	v_pk_add_f32 v[152:153], v[42:43], v[158:159] op_sel_hi:[1,0] neg_lo:[0,1] neg_hi:[0,1]
	v_pk_add_f32 v[166:167], v[22:23], v[172:173] op_sel_hi:[1,0] neg_lo:[0,1] neg_hi:[0,1]
	v_pk_add_f32 v[180:181], v[6:7], v[186:187] op_sel_hi:[1,0] neg_lo:[0,1] neg_hi:[0,1]
	v_pk_fma_f32 v[146:147], v[138:139], v[138:139], v[146:147]
	v_pk_fma_f32 v[160:161], v[152:153], v[152:153], v[160:161]
	v_pk_fma_f32 v[174:175], v[166:167], v[166:167], v[174:175]
	v_pk_fma_f32 v[188:189], v[180:181], v[180:181], v[188:189]
	v_pk_add_f32 v[140:141], v[52:53], v[144:145] op_sel_hi:[1,0] neg_lo:[0,1] neg_hi:[0,1]
	v_pk_add_f32 v[154:155], v[36:37], v[158:159] op_sel_hi:[1,0] neg_lo:[0,1] neg_hi:[0,1]
	v_pk_add_f32 v[168:169], v[16:17], v[172:173] op_sel_hi:[1,0] neg_lo:[0,1] neg_hi:[0,1]
	v_pk_add_f32 v[182:183], v[0:1], v[186:187] op_sel_hi:[1,0] neg_lo:[0,1] neg_hi:[0,1]
	v_pk_fma_f32 v[146:147], v[140:141], v[140:141], v[146:147]
	v_pk_fma_f32 v[160:161], v[154:155], v[154:155], v[160:161]
	v_pk_fma_f32 v[174:175], v[168:169], v[168:169], v[174:175]
	v_pk_fma_f32 v[188:189], v[182:183], v[182:183], v[188:189]
	v_pk_add_f32 v[142:143], v[54:55], v[144:145] op_sel_hi:[1,0] neg_lo:[0,1] neg_hi:[0,1]
	v_pk_add_f32 v[156:157], v[38:39], v[158:159] op_sel_hi:[1,0] neg_lo:[0,1] neg_hi:[0,1]
	v_pk_add_f32 v[170:171], v[18:19], v[172:173] op_sel_hi:[1,0] neg_lo:[0,1] neg_hi:[0,1]
	v_pk_add_f32 v[184:185], v[2:3], v[186:187] op_sel_hi:[1,0] neg_lo:[0,1] neg_hi:[0,1]
	v_pk_fma_f32 v[146:147], v[142:143], v[142:143], v[146:147]
	v_pk_fma_f32 v[160:161], v[156:157], v[156:157], v[160:161]
	v_pk_fma_f32 v[174:175], v[170:171], v[170:171], v[174:175]
	v_pk_fma_f32 v[188:189], v[184:185], v[184:185], v[188:189]
	v_add_f32_e32 v145, v146, v147
	v_add_f32_e32 v159, v160, v161
	v_add_f32_e32 v173, v174, v175
	v_add_f32_e32 v187, v188, v189
	v_mov_b32_e32 v148, v145
	v_mov_b32_e32 v162, v159
	v_mov_b32_e32 v176, v173
	v_mov_b32_e32 v190, v187
	v_permlane16_swap_b32 v148, v145
	v_permlane16_swap_b32 v162, v159
	v_permlane16_swap_b32 v176, v173
	v_permlane16_swap_b32 v190, v187
	v_add_f32_e32 v145, v145, v148
	v_add_f32_e32 v159, v159, v162
	v_add_f32_e32 v173, v173, v176
	v_add_f32_e32 v187, v187, v190
	v_mov_b32_e32 v148, v145
	v_mov_b32_e32 v162, v159
	v_mov_b32_e32 v176, v173
	v_mov_b32_e32 v190, v187
	v_permlane32_swap_b32 v148, v145
	v_permlane32_swap_b32 v162, v159
	v_permlane32_swap_b32 v176, v173
	v_permlane32_swap_b32 v190, v187
	v_add_f32_e32 v145, v145, v148
	v_add_f32_e32 v159, v159, v162
	v_add_f32_e32 v173, v173, v176
	v_add_f32_e32 v187, v187, v190
	s_and_saveexec_b64 s[4:5], vcc
	ds_write_b64 v132, v[144:145] offset:4096
	ds_write_b64 v132, v[158:159] offset:4608
	ds_write_b64 v132, v[172:173] offset:5120
	ds_write_b64 v132, v[186:187] offset:5632
	s_or_b64 exec, exec, s[4:5]
	v_readlane_b32 s2, v251, 8
	s_waitcnt lgkmcnt(0)
	s_barrier
	v_cmp_gt_i32_e64 s[4:5], 32, v32
	v_and_or_b32 v134, v32, 31, s2
	v_add_u32_e32 v132, s14, v134
	v_ashrrev_i32_e32 v133, 31, v132
	s_and_saveexec_b64 s[2:3], s[4:5]
	s_cbranch_execz .LBB0_451
	s_waitcnt lgkmcnt(0)
	v_mov_b32_e32 v146, 0x24970
	ds_read_b32 v146, v146
	v_lshl_add_u32 v135, v134, 5, 0
	ds_read_b128 v[136:139], v135
	ds_read_b128 v[140:143], v135 offset:16
	v_readlane_b32 s6, v252, 14
	v_readlane_b32 s7, v252, 15
	s_ashr_i32 s35, s34, 31
	s_waitcnt lgkmcnt(1)
	v_add_f32_e32 v135, v136, v138
	s_waitcnt lgkmcnt(0)
	v_add_f32_e32 v135, v135, v140
	v_add_f32_e32 v135, v135, v142
	v_fmamk_f32 v136, v135, 0xbe800000, v136
	v_fmac_f32_e32 v138, 0xbe800000, v135
	v_fmamk_f32 v140, v135, 0xbe800000, v140
	v_fmac_f32_e32 v142, 0xbe800000, v135
	v_mul_f32_e32 v147, v136, v136
	v_mul_f32_e32 v149, v138, v138
	v_mul_f32_e32 v151, v140, v140
	v_mul_f32_e32 v153, v142, v142
	v_mov_b32_e32 v146, v137
	v_mov_b32_e32 v148, v139
	v_mov_b32_e32 v150, v141
	v_mov_b32_e32 v152, v143
	v_pk_add_f32 v[136:137], v[146:147], v[148:149]
	v_pk_add_f32 v[138:139], v[150:151], v[152:153]
	v_mul_f32_e32 v144, 0x3e800000, v135
	v_pk_add_f32 v[136:137], v[136:137], v[138:139]
	v_lshlrev_b64 v[138:139], 5, v[132:133]
	v_fmac_f32_e32 v136, 0x42800000, v137
	v_lshl_add_u64 v[138:139], s[6:7], 0, v[138:139]
	v_lshl_add_u64 v[138:139], s[34:35], 3, v[138:139]
	v_mov_b32_e32 v145, v136
	v_readfirstlane_b32 s98, v146
	s_nop 3
	s_cmp_eq_u32 s98, 0
	s_cbranch_scc1 .Lslot_sc1
	global_store_dwordx2 v[138:139], v[144:145], off
	s_branch .Lslot_done
